# P5 GEMM epilogue with f32 residual base: 16 serialized load-wait-add-store round trips per tile replaced by one 16-load batch parked in the unused bf16-base registers + refills 4 steps ahead (steps 8-
# baseline (speedup 1.0000x reference)
; __device__ __forceinline__ unsigned cvt_pk_bf16(float lo, float hi) { return pk2(lo, hi); }
;     __device__ __forceinline__ void operator()(const f32x4 (&acc)[2][2][4][2], const Unit& u, long coff, int wr, int wc, int fr, int fq, LAS unsigned char* xl) const {
;     ...
;             for (int m = 0; m < 4; ++m) { const int row = rowb + ai * HALF + m * 16; const size_t off = (size_t)row * ldc + col0; float ss = 0.f;
; #pragma unroll
;                 for (int bj = 0; bj < 2; ++bj) { f32x4 b0, b1;
;                     if (basef) { b0 = *(const f32x4*)(basef + off + bj * HALF); b1 = *(const f32x4*)(basef + off + bj * HALF + 4); }
;                     else { const u32x4 h4 = hb[ai][m][bj]; b0 = (f32x4){bflo(h4.x), bfhi(h4.x), bflo(h4.y), bfhi(h4.y)}; b1 = (f32x4){bflo(h4.z), bfhi(h4.z), bflo(h4.w), bfhi(h4.w)}; }
;                     const f32x4 o0 = b0 + acc[ai][bj][m][0], o1 = b1 + acc[ai][bj][m][1];
;                     ss += ((o0[0] * o0[0] + o0[1] * o0[1]) + (o0[2] * o0[2] + o0[3] * o0[3])) + ((o1[0] * o1[0] + o1[1] * o1[1]) + (o1[2] * o1[2] + o1[3] * o1[3]));
;                     u32x4 w; w.x = cvt_pk_bf16(o0[0], o0[1]); w.y = cvt_pk_bf16(o0[2], o0[3]); w.z = cvt_pk_bf16(o1[0], o1[1]); w.w = cvt_pk_bf16(o1[2], o1[3]);
;                     *(u32x4*)(HB + off + bj * HALF) = w; }
.LBB0_1073:
	v_lshl_add_u64 v[232:233], v[192:193], 0, v[222:223]
	s_and_b64 vcc, exec, s[4:5]
	v_lshl_add_u64 v[230:231], v[232:233], 2, s[60:61]
	s_cbranch_vccnz .LBB0_1140
	v_add_co_u32_e32 v192, vcc, 0x10000, v230
	s_nop 1
	v_addc_co_u32_e32 v193, vcc, 0, v231, vcc
	v_add_co_u32_e32 v194, vcc, 0x20000, v230
	s_nop 1
	v_addc_co_u32_e32 v195, vcc, 0, v231, vcc
	v_add_co_u32_e32 v196, vcc, 0x30000, v230
	s_nop 1
	v_addc_co_u32_e32 v197, vcc, 0, v231, vcc
	global_load_dwordx4 v[188:191], v[230:231], off
	global_load_dwordx4 v[184:187], v[230:231], off offset:16
	global_load_dwordx4 v[180:183], v[230:231], off offset:512
	global_load_dwordx4 v[176:179], v[230:231], off offset:528
	global_load_dwordx4 v[172:175], v[192:193], off
	global_load_dwordx4 v[168:171], v[192:193], off offset:16
	global_load_dwordx4 v[164:167], v[192:193], off offset:512
	global_load_dwordx4 v[160:163], v[192:193], off offset:528
	global_load_dwordx4 v[148:151], v[194:195], off
	global_load_dwordx4 v[136:139], v[194:195], off offset:16
	global_load_dwordx4 v[124:127], v[194:195], off offset:512
	global_load_dwordx4 v[112:115], v[194:195], off offset:528
	global_load_dwordx4 v[100:103], v[196:197], off
	global_load_dwordx4 v[88:91], v[196:197], off offset:16
	global_load_dwordx4 v[76:79], v[196:197], off offset:512
	global_load_dwordx4 v[64:67], v[196:197], off offset:528
	s_waitcnt vmcnt(14)
	v_mov_b64 v[192:193], v[188:189]
	v_mov_b64 v[194:195], v[190:191]
	v_mov_b64 v[196:197], v[184:185]
	v_mov_b64 v[198:199], v[186:187]
	s_cbranch_execnz .LBB0_1076

; __device__ __forceinline__ unsigned cvt_pk_bf16(float lo, float hi) { return pk2(lo, hi); }
;     __device__ __forceinline__ void operator()(const f32x4 (&acc)[2][2][4][2], const Unit& u, long coff, int wr, int wc, int fr, int fq, LAS unsigned char* xl) const {
;     ...
;                 for (int bj = 0; bj < 2; ++bj) { f32x4 b0, b1;
;                     if (basef) { b0 = *(const f32x4*)(basef + off + bj * HALF); b1 = *(const f32x4*)(basef + off + bj * HALF + 4); }
;                     else { const u32x4 h4 = hb[ai][m][bj]; b0 = (f32x4){bflo(h4.x), bfhi(h4.x), bflo(h4.y), bfhi(h4.y)}; b1 = (f32x4){bflo(h4.z), bfhi(h4.z), bflo(h4.w), bfhi(h4.w)}; }
;                     const f32x4 o0 = b0 + acc[ai][bj][m][0], o1 = b1 + acc[ai][bj][m][1];
;                     ss += ((o0[0] * o0[0] + o0[1] * o0[1]) + (o0[2] * o0[2] + o0[3] * o0[3])) + ((o1[0] * o1[0] + o1[1] * o1[1]) + (o1[2] * o1[2] + o1[3] * o1[3]));
;                     u32x4 w; w.x = cvt_pk_bf16(o0[0], o0[1]); w.y = cvt_pk_bf16(o0[2], o0[3]); w.z = cvt_pk_bf16(o1[0], o1[1]); w.w = cvt_pk_bf16(o1[2], o1[3]);
;                     *(u32x4*)(HB + off + bj * HALF) = w; }
.LBB0_1076:
	v_readlane_b32 s34, v253, 21
	v_pk_add_f32 v[190:191], v[158:159], v[194:195]
	v_pk_add_f32 v[194:195], v[156:157], v[192:193]
	v_pk_add_f32 v[192:193], v[154:155], v[198:199]
	v_pk_add_f32 v[196:197], v[152:153], v[196:197]
	v_readlane_b32 s35, v253, 22
	v_cvt_pk_bf16_f32 v152, v194, v195
	v_cvt_pk_bf16_f32 v153, v190, v191
	v_cvt_pk_bf16_f32 v154, v196, v197
	v_cvt_pk_bf16_f32 v155, v192, v193
	v_lshl_add_u64 v[188:189], v[232:233], 1, s[34:35]
	s_and_b64 vcc, exec, s[4:5]
	global_store_dwordx4 v[188:189], v[152:155], off
	s_cbranch_vccnz .LBB0_1141
	s_waitcnt vmcnt(12)
	v_mov_b64 v[152:153], v[180:181]
	v_mov_b64 v[154:155], v[182:183]
	v_mov_b64 v[156:157], v[176:177]
	v_mov_b64 v[158:159], v[178:179]
	s_cbranch_execnz .LBB0_1079

; __device__ __forceinline__ unsigned cvt_pk_bf16(float lo, float hi) { return pk2(lo, hi); }
;     __device__ __forceinline__ void operator()(const f32x4 (&acc)[2][2][4][2], const Unit& u, long coff, int wr, int wc, int fr, int fq, LAS unsigned char* xl) const {
;     ...
;             for (int m = 0; m < 4; ++m) { const int row = rowb + ai * HALF + m * 16; const size_t off = (size_t)row * ldc + col0; float ss = 0.f;
;     ...
;                     const f32x4 o0 = b0 + acc[ai][bj][m][0], o1 = b1 + acc[ai][bj][m][1];
;                     ss += ((o0[0] * o0[0] + o0[1] * o0[1]) + (o0[2] * o0[2] + o0[3] * o0[3])) + ((o1[0] * o1[0] + o1[1] * o1[1]) + (o1[2] * o1[2] + o1[3] * o1[3]));
;                     u32x4 w; w.x = cvt_pk_bf16(o0[0], o0[1]); w.y = cvt_pk_bf16(o0[2], o0[3]); w.z = cvt_pk_bf16(o1[0], o1[1]); w.w = cvt_pk_bf16(o1[2], o1[3]);
;                     *(u32x4*)(HB + off + bj * HALF) = w; }
;                 ss += __shfl_xor(ss, 16); ss += __shfl_xor(ss, 32);
;                 if (fq == 0) PS[(size_t)row * 16 + u.pn * 4 + wc] = ss; }
.LBB0_1079:
	v_mul_f32_e32 v184, v195, v195
	v_mul_f32_e32 v185, v191, v191
	v_fmac_f32_e32 v184, v194, v194
	v_fmac_f32_e32 v185, v190, v190
	v_pk_add_f32 v[146:147], v[146:147], v[154:155]
	v_pk_add_f32 v[144:145], v[144:145], v[152:153]
	v_add_f32_e32 v184, v184, v185
	v_mul_f32_e32 v185, v197, v197
	v_mul_f32_e32 v186, v193, v193
	v_pk_add_f32 v[154:155], v[140:141], v[156:157]
	v_mul_f32_e32 v140, v145, v145
	v_mul_f32_e32 v141, v147, v147
	v_fmac_f32_e32 v185, v196, v196
	v_fmac_f32_e32 v186, v192, v192
	v_pk_add_f32 v[152:153], v[142:143], v[158:159]
	v_fmac_f32_e32 v140, v144, v144
	v_fmac_f32_e32 v141, v146, v146
	v_add_f32_e32 v185, v185, v186
	v_and_b32_e32 v186, 64, v247
	v_add_f32_e32 v140, v140, v141
	v_mul_f32_e32 v141, v155, v155
	v_mul_f32_e32 v142, v153, v153
	v_add_f32_e32 v185, v184, v185
	v_xor_b32_e32 v184, 16, v247
	v_add_u32_e32 v186, 64, v186
	v_fmac_f32_e32 v141, v154, v154
	v_fmac_f32_e32 v142, v152, v152
	v_cmp_lt_i32_e32 vcc, v184, v186
	v_add_f32_e32 v141, v141, v142
	v_add_f32_e32 v140, v140, v141
	v_cndmask_b32_e32 v184, v247, v184, vcc
	v_lshlrev_b32_e32 v184, 2, v184
	v_add_f32_e32 v140, v185, v140
	ds_bpermute_b32 v141, v184, v140
	v_xor_b32_e32 v187, 32, v247
	v_cmp_lt_i32_e32 vcc, v187, v186
	s_lshl_b32 s34, s10, 2
	s_ashr_i32 s35, s34, 31
	v_cndmask_b32_e32 v186, v247, v187, vcc
	v_lshlrev_b32_e32 v158, 2, v186
	s_waitcnt lgkmcnt(0)
	v_add_f32_e32 v140, v140, v141
	ds_bpermute_b32 v141, v158, v140
	v_cvt_pk_bf16_f32 v142, v144, v145
	v_cvt_pk_bf16_f32 v143, v146, v147
	v_cvt_pk_bf16_f32 v144, v154, v155
	v_cvt_pk_bf16_f32 v145, v152, v153
	global_store_dwordx4 v[188:189], v[142:145], off offset:256
	s_and_saveexec_b64 s[36:37], s[0:1]
	s_cbranch_execz .LBB0_1081
	v_lshlrev_b64 v[142:143], 6, v[220:221]
	v_lshl_add_u64 v[142:143], s[26:27], 0, v[142:143]
	v_lshl_add_u64 v[142:143], s[34:35], 2, v[142:143]
	s_lshl_b32 s10, s45, 2
	v_lshl_add_u64 v[142:143], v[142:143], 0, s[10:11]
	s_waitcnt lgkmcnt(0)
	v_add_f32_e32 v140, v140, v141
	global_store_dword v[142:143], v140, off
.LBB0_1081:
	s_or_b64 exec, exec, s[36:37]
	s_waitcnt lgkmcnt(0)
	v_lshlrev_b64 v[140:141], 10, v[228:229]
	v_lshl_add_u64 v[154:155], v[140:141], 0, v[222:223]
	s_and_b64 vcc, exec, s[4:5]
	v_lshl_add_u64 v[152:153], v[154:155], 2, s[60:61]
	s_cbranch_vccnz .LBB0_1142
	s_waitcnt vmcnt(10)
	v_mov_b64 v[140:141], v[172:173]
	v_mov_b64 v[142:143], v[174:175]
	v_mov_b64 v[144:145], v[168:169]
	v_mov_b64 v[146:147], v[170:171]
	s_cbranch_execnz .LBB0_1084

; __device__ __forceinline__ unsigned cvt_pk_bf16(float lo, float hi) { return pk2(lo, hi); }
;     __device__ __forceinline__ void operator()(const f32x4 (&acc)[2][2][4][2], const Unit& u, long coff, int wr, int wc, int fr, int fq, LAS unsigned char* xl) const {
;     ...
;                 for (int bj = 0; bj < 2; ++bj) { f32x4 b0, b1;
;                     if (basef) { b0 = *(const f32x4*)(basef + off + bj * HALF); b1 = *(const f32x4*)(basef + off + bj * HALF + 4); }
;                     else { const u32x4 h4 = hb[ai][m][bj]; b0 = (f32x4){bflo(h4.x), bfhi(h4.x), bflo(h4.y), bfhi(h4.y)}; b1 = (f32x4){bflo(h4.z), bfhi(h4.z), bflo(h4.w), bfhi(h4.w)}; }
;                     const f32x4 o0 = b0 + acc[ai][bj][m][0], o1 = b1 + acc[ai][bj][m][1];
;                     ss += ((o0[0] * o0[0] + o0[1] * o0[1]) + (o0[2] * o0[2] + o0[3] * o0[3])) + ((o1[0] * o1[0] + o1[1] * o1[1]) + (o1[2] * o1[2] + o1[3] * o1[3]));
;                     u32x4 w; w.x = cvt_pk_bf16(o0[0], o0[1]); w.y = cvt_pk_bf16(o0[2], o0[3]); w.z = cvt_pk_bf16(o1[0], o1[1]); w.w = cvt_pk_bf16(o1[2], o1[3]);
;                     *(u32x4*)(HB + off + bj * HALF) = w; }
.LBB0_1084:
	v_readlane_b32 s36, v253, 21
	v_pk_add_f32 v[142:143], v[134:135], v[142:143]
	v_pk_add_f32 v[156:157], v[132:133], v[140:141]
	v_pk_add_f32 v[146:147], v[130:131], v[146:147]
	v_pk_add_f32 v[144:145], v[128:129], v[144:145]
	v_readlane_b32 s37, v253, 22
	v_cvt_pk_bf16_f32 v128, v156, v157
	v_cvt_pk_bf16_f32 v129, v142, v143
	v_cvt_pk_bf16_f32 v130, v144, v145
	v_cvt_pk_bf16_f32 v131, v146, v147
	v_lshl_add_u64 v[140:141], v[154:155], 1, s[36:37]
	s_and_b64 vcc, exec, s[4:5]
	global_store_dwordx4 v[140:141], v[128:131], off
	s_cbranch_vccnz .LBB0_1143
	s_waitcnt vmcnt(8)
	v_mov_b64 v[128:129], v[164:165]
	v_mov_b64 v[130:131], v[166:167]
	v_mov_b64 v[132:133], v[160:161]
	v_mov_b64 v[134:135], v[162:163]
	s_cbranch_execnz .LBB0_1087

; __device__ __forceinline__ unsigned cvt_pk_bf16(float lo, float hi) { return pk2(lo, hi); }
;     __device__ __forceinline__ void operator()(const f32x4 (&acc)[2][2][4][2], const Unit& u, long coff, int wr, int wc, int fr, int fq, LAS unsigned char* xl) const {
;     ...
;             for (int m = 0; m < 4; ++m) { const int row = rowb + ai * HALF + m * 16; const size_t off = (size_t)row * ldc + col0; float ss = 0.f;
;     ...
;                     const f32x4 o0 = b0 + acc[ai][bj][m][0], o1 = b1 + acc[ai][bj][m][1];
;                     ss += ((o0[0] * o0[0] + o0[1] * o0[1]) + (o0[2] * o0[2] + o0[3] * o0[3])) + ((o1[0] * o1[0] + o1[1] * o1[1]) + (o1[2] * o1[2] + o1[3] * o1[3]));
;                     u32x4 w; w.x = cvt_pk_bf16(o0[0], o0[1]); w.y = cvt_pk_bf16(o0[2], o0[3]); w.z = cvt_pk_bf16(o1[0], o1[1]); w.w = cvt_pk_bf16(o1[2], o1[3]);
;                     *(u32x4*)(HB + off + bj * HALF) = w; }
;                 ss += __shfl_xor(ss, 16); ss += __shfl_xor(ss, 32);
;                 if (fq == 0) PS[(size_t)row * 16 + u.pn * 4 + wc] = ss; }
.LBB0_1087:
	v_mul_f32_e32 v152, v157, v157
	v_mul_f32_e32 v143, v143, v143
	v_pk_add_f32 v[122:123], v[122:123], v[130:131]
	v_pk_add_f32 v[120:121], v[120:121], v[128:129]
	v_fmac_f32_e32 v152, v156, v156
	v_fmac_f32_e32 v143, v142, v142
	v_pk_add_f32 v[130:131], v[116:117], v[132:133]
	v_mul_f32_e32 v116, v121, v121
	v_mul_f32_e32 v117, v123, v123
	v_add_f32_e32 v142, v152, v143
	v_mul_f32_e32 v143, v145, v145
	v_pk_add_f32 v[128:129], v[118:119], v[134:135]
	v_fmac_f32_e32 v116, v120, v120
	v_fmac_f32_e32 v117, v122, v122
	v_fmac_f32_e32 v143, v144, v144
	v_mul_f32_e32 v144, v147, v147
	v_add_f32_e32 v116, v116, v117
	v_mul_f32_e32 v117, v131, v131
	v_mul_f32_e32 v118, v129, v129
	v_fmac_f32_e32 v144, v146, v146
	v_fmac_f32_e32 v117, v130, v130
	v_fmac_f32_e32 v118, v128, v128
	v_add_f32_e32 v143, v143, v144
	v_add_f32_e32 v117, v117, v118
	v_add_f32_e32 v142, v142, v143
	v_add_f32_e32 v116, v116, v117
	v_add_f32_e32 v116, v142, v116
	ds_bpermute_b32 v117, v184, v116
	v_cvt_pk_bf16_f32 v118, v120, v121
	v_cvt_pk_bf16_f32 v119, v122, v123
	v_cvt_pk_bf16_f32 v120, v130, v131
	v_cvt_pk_bf16_f32 v121, v128, v129
	s_waitcnt lgkmcnt(0)
	v_add_f32_e32 v116, v116, v117
	ds_bpermute_b32 v117, v158, v116
	global_store_dwordx4 v[140:141], v[118:121], off offset:256
	s_and_saveexec_b64 s[36:37], s[0:1]
	s_cbranch_execz .LBB0_1089
	v_lshlrev_b64 v[118:119], 6, v[228:229]
	v_lshl_add_u64 v[118:119], s[26:27], 0, v[118:119]
	v_lshl_add_u64 v[118:119], s[34:35], 2, v[118:119]
	s_lshl_b32 s10, s45, 2
	v_lshl_add_u64 v[118:119], v[118:119], 0, s[10:11]
	s_waitcnt lgkmcnt(0)
	v_add_f32_e32 v116, v116, v117
	global_store_dword v[118:119], v116, off
.LBB0_1089:
	s_or_b64 exec, exec, s[36:37]
	s_waitcnt lgkmcnt(0)
	v_lshlrev_b64 v[116:117], 10, v[226:227]
	v_lshl_add_u64 v[130:131], v[116:117], 0, v[222:223]
	s_and_b64 vcc, exec, s[4:5]
	v_lshl_add_u64 v[128:129], v[130:131], 2, s[60:61]
	s_cbranch_vccnz .LBB0_1144
	s_waitcnt vmcnt(6)
	v_mov_b64 v[116:117], v[148:149]
	v_mov_b64 v[118:119], v[150:151]
	v_mov_b64 v[120:121], v[136:137]
	v_mov_b64 v[122:123], v[138:139]
	v_add_co_u32_e32 v148, vcc, 0x60000, v128
	s_nop 1
	v_addc_co_u32_e32 v149, vcc, 0, v129, vcc
	global_load_dwordx4 v[136:139], v[148:149], off offset:16
	global_load_dwordx4 v[148:151], v[148:149], off
	s_cbranch_execnz .LBB0_1092

; __device__ __forceinline__ unsigned cvt_pk_bf16(float lo, float hi) { return pk2(lo, hi); }
;     __device__ __forceinline__ void operator()(const f32x4 (&acc)[2][2][4][2], const Unit& u, long coff, int wr, int wc, int fr, int fq, LAS unsigned char* xl) const {
;     ...
;                 for (int bj = 0; bj < 2; ++bj) { f32x4 b0, b1;
;                     if (basef) { b0 = *(const f32x4*)(basef + off + bj * HALF); b1 = *(const f32x4*)(basef + off + bj * HALF + 4); }
;                     else { const u32x4 h4 = hb[ai][m][bj]; b0 = (f32x4){bflo(h4.x), bfhi(h4.x), bflo(h4.y), bfhi(h4.y)}; b1 = (f32x4){bflo(h4.z), bfhi(h4.z), bflo(h4.w), bfhi(h4.w)}; }
;                     const f32x4 o0 = b0 + acc[ai][bj][m][0], o1 = b1 + acc[ai][bj][m][1];
;                     ss += ((o0[0] * o0[0] + o0[1] * o0[1]) + (o0[2] * o0[2] + o0[3] * o0[3])) + ((o1[0] * o1[0] + o1[1] * o1[1]) + (o1[2] * o1[2] + o1[3] * o1[3]));
;                     u32x4 w; w.x = cvt_pk_bf16(o0[0], o0[1]); w.y = cvt_pk_bf16(o0[2], o0[3]); w.z = cvt_pk_bf16(o1[0], o1[1]); w.w = cvt_pk_bf16(o1[2], o1[3]);
;                     *(u32x4*)(HB + off + bj * HALF) = w; }
.LBB0_1092:
	v_readlane_b32 s36, v253, 21
	v_pk_add_f32 v[118:119], v[110:111], v[118:119]
	v_pk_add_f32 v[132:133], v[108:109], v[116:117]
	v_pk_add_f32 v[122:123], v[106:107], v[122:123]
	v_pk_add_f32 v[120:121], v[104:105], v[120:121]
	v_readlane_b32 s37, v253, 22
	v_cvt_pk_bf16_f32 v104, v132, v133
	v_cvt_pk_bf16_f32 v105, v118, v119
	v_cvt_pk_bf16_f32 v106, v120, v121
	v_cvt_pk_bf16_f32 v107, v122, v123
	v_lshl_add_u64 v[116:117], v[130:131], 1, s[36:37]
	s_and_b64 vcc, exec, s[4:5]
	global_store_dwordx4 v[116:117], v[104:107], off
	s_cbranch_vccnz .LBB0_1145
	s_waitcnt vmcnt(6)
	v_mov_b64 v[104:105], v[124:125]
	v_mov_b64 v[106:107], v[126:127]
	v_mov_b64 v[108:109], v[112:113]
	v_mov_b64 v[110:111], v[114:115]
	v_add_co_u32_e32 v124, vcc, 0x60000, v128
	s_nop 1
	v_addc_co_u32_e32 v125, vcc, 0, v129, vcc
	global_load_dwordx4 v[112:115], v[124:125], off offset:528
	global_load_dwordx4 v[124:127], v[124:125], off offset:512
	s_cbranch_execnz .LBB0_1095

; __device__ __forceinline__ unsigned cvt_pk_bf16(float lo, float hi) { return pk2(lo, hi); }
;     __device__ __forceinline__ void operator()(const f32x4 (&acc)[2][2][4][2], const Unit& u, long coff, int wr, int wc, int fr, int fq, LAS unsigned char* xl) const {
;     ...
;             for (int m = 0; m < 4; ++m) { const int row = rowb + ai * HALF + m * 16; const size_t off = (size_t)row * ldc + col0; float ss = 0.f;
;     ...
;                     const f32x4 o0 = b0 + acc[ai][bj][m][0], o1 = b1 + acc[ai][bj][m][1];
;                     ss += ((o0[0] * o0[0] + o0[1] * o0[1]) + (o0[2] * o0[2] + o0[3] * o0[3])) + ((o1[0] * o1[0] + o1[1] * o1[1]) + (o1[2] * o1[2] + o1[3] * o1[3]));
;                     u32x4 w; w.x = cvt_pk_bf16(o0[0], o0[1]); w.y = cvt_pk_bf16(o0[2], o0[3]); w.z = cvt_pk_bf16(o1[0], o1[1]); w.w = cvt_pk_bf16(o1[2], o1[3]);
;                     *(u32x4*)(HB + off + bj * HALF) = w; }
;                 ss += __shfl_xor(ss, 16); ss += __shfl_xor(ss, 32);
;                 if (fq == 0) PS[(size_t)row * 16 + u.pn * 4 + wc] = ss; }
.LBB0_1095:
	v_mul_f32_e32 v128, v133, v133
	v_mul_f32_e32 v119, v119, v119
	v_pk_add_f32 v[98:99], v[98:99], v[106:107]
	v_pk_add_f32 v[96:97], v[96:97], v[104:105]
	v_fmac_f32_e32 v128, v132, v132
	v_fmac_f32_e32 v119, v118, v118
	v_pk_add_f32 v[106:107], v[92:93], v[108:109]
	v_mul_f32_e32 v92, v97, v97
	v_mul_f32_e32 v93, v99, v99
	v_add_f32_e32 v118, v128, v119
	v_mul_f32_e32 v119, v121, v121
	v_pk_add_f32 v[104:105], v[94:95], v[110:111]
	v_fmac_f32_e32 v92, v96, v96
	v_fmac_f32_e32 v93, v98, v98
	v_fmac_f32_e32 v119, v120, v120
	v_mul_f32_e32 v120, v123, v123
	v_add_f32_e32 v92, v92, v93
	v_mul_f32_e32 v93, v107, v107
	v_mul_f32_e32 v94, v105, v105
	v_fmac_f32_e32 v120, v122, v122
	v_fmac_f32_e32 v93, v106, v106
	v_fmac_f32_e32 v94, v104, v104
	v_add_f32_e32 v119, v119, v120
	v_add_f32_e32 v93, v93, v94
	v_add_f32_e32 v118, v118, v119
	v_add_f32_e32 v92, v92, v93
	v_add_f32_e32 v92, v118, v92
	ds_bpermute_b32 v93, v184, v92
	v_cvt_pk_bf16_f32 v94, v96, v97
	v_cvt_pk_bf16_f32 v95, v98, v99
	v_cvt_pk_bf16_f32 v96, v106, v107
	v_cvt_pk_bf16_f32 v97, v104, v105
	s_waitcnt lgkmcnt(0)
	v_add_f32_e32 v92, v92, v93
	ds_bpermute_b32 v93, v158, v92
	global_store_dwordx4 v[116:117], v[94:97], off offset:256
	s_and_saveexec_b64 s[36:37], s[0:1]
	s_cbranch_execz .LBB0_1097
	v_lshlrev_b64 v[94:95], 6, v[226:227]
	v_lshl_add_u64 v[94:95], s[26:27], 0, v[94:95]
	v_lshl_add_u64 v[94:95], s[34:35], 2, v[94:95]
	s_lshl_b32 s10, s45, 2
	v_lshl_add_u64 v[94:95], v[94:95], 0, s[10:11]
	s_waitcnt lgkmcnt(0)
	v_add_f32_e32 v92, v92, v93
	global_store_dword v[94:95], v92, off
.LBB0_1097:
	s_or_b64 exec, exec, s[36:37]
	s_waitcnt lgkmcnt(0)
	v_lshlrev_b64 v[92:93], 10, v[224:225]
	v_lshl_add_u64 v[106:107], v[92:93], 0, v[222:223]
	s_and_b64 vcc, exec, s[4:5]
	v_lshl_add_u64 v[104:105], v[106:107], 2, s[60:61]
	s_cbranch_vccnz .LBB0_1146
	s_waitcnt vmcnt(6)
	v_mov_b64 v[92:93], v[100:101]
	v_mov_b64 v[94:95], v[102:103]
	v_mov_b64 v[96:97], v[88:89]
	v_mov_b64 v[98:99], v[90:91]
	v_add_co_u32_e32 v100, vcc, 0x60000, v104
	s_nop 1
	v_addc_co_u32_e32 v101, vcc, 0, v105, vcc
	global_load_dwordx4 v[88:91], v[100:101], off offset:16
	global_load_dwordx4 v[100:103], v[100:101], off
	s_cbranch_execnz .LBB0_1100

; __device__ __forceinline__ unsigned cvt_pk_bf16(float lo, float hi) { return pk2(lo, hi); }
;     __device__ __forceinline__ void operator()(const f32x4 (&acc)[2][2][4][2], const Unit& u, long coff, int wr, int wc, int fr, int fq, LAS unsigned char* xl) const {
;     ...
;                 for (int bj = 0; bj < 2; ++bj) { f32x4 b0, b1;
;                     if (basef) { b0 = *(const f32x4*)(basef + off + bj * HALF); b1 = *(const f32x4*)(basef + off + bj * HALF + 4); }
;                     else { const u32x4 h4 = hb[ai][m][bj]; b0 = (f32x4){bflo(h4.x), bfhi(h4.x), bflo(h4.y), bfhi(h4.y)}; b1 = (f32x4){bflo(h4.z), bfhi(h4.z), bflo(h4.w), bfhi(h4.w)}; }
;                     const f32x4 o0 = b0 + acc[ai][bj][m][0], o1 = b1 + acc[ai][bj][m][1];
;                     ss += ((o0[0] * o0[0] + o0[1] * o0[1]) + (o0[2] * o0[2] + o0[3] * o0[3])) + ((o1[0] * o1[0] + o1[1] * o1[1]) + (o1[2] * o1[2] + o1[3] * o1[3]));
;                     u32x4 w; w.x = cvt_pk_bf16(o0[0], o0[1]); w.y = cvt_pk_bf16(o0[2], o0[3]); w.z = cvt_pk_bf16(o1[0], o1[1]); w.w = cvt_pk_bf16(o1[2], o1[3]);
;                     *(u32x4*)(HB + off + bj * HALF) = w; }
.LBB0_1100:
	v_readlane_b32 s36, v253, 21
	v_pk_add_f32 v[94:95], v[86:87], v[94:95]
	v_pk_add_f32 v[108:109], v[84:85], v[92:93]
	v_pk_add_f32 v[98:99], v[82:83], v[98:99]
	v_pk_add_f32 v[96:97], v[80:81], v[96:97]
	v_readlane_b32 s37, v253, 22
	v_cvt_pk_bf16_f32 v80, v108, v109
	v_cvt_pk_bf16_f32 v81, v94, v95
	v_cvt_pk_bf16_f32 v82, v96, v97
	v_cvt_pk_bf16_f32 v83, v98, v99
	v_lshl_add_u64 v[92:93], v[106:107], 1, s[36:37]
	s_and_b64 vcc, exec, s[4:5]
	global_store_dwordx4 v[92:93], v[80:83], off
	s_cbranch_vccnz .LBB0_1147
	s_waitcnt vmcnt(6)
	v_mov_b64 v[80:81], v[76:77]
	v_mov_b64 v[82:83], v[78:79]
	v_mov_b64 v[84:85], v[64:65]
	v_mov_b64 v[86:87], v[66:67]
	v_add_co_u32_e32 v76, vcc, 0x60000, v104
	s_nop 1
	v_addc_co_u32_e32 v77, vcc, 0, v105, vcc
	global_load_dwordx4 v[64:67], v[76:77], off offset:528
	global_load_dwordx4 v[76:79], v[76:77], off offset:512
	s_cbranch_execnz .LBB0_1103

; __device__ __forceinline__ unsigned cvt_pk_bf16(float lo, float hi) { return pk2(lo, hi); }
;     __device__ __forceinline__ void operator()(const f32x4 (&acc)[2][2][4][2], const Unit& u, long coff, int wr, int wc, int fr, int fq, LAS unsigned char* xl) const {
;     ...
;             for (int m = 0; m < 4; ++m) { const int row = rowb + ai * HALF + m * 16; const size_t off = (size_t)row * ldc + col0; float ss = 0.f;
;     ...
;                     const f32x4 o0 = b0 + acc[ai][bj][m][0], o1 = b1 + acc[ai][bj][m][1];
;                     ss += ((o0[0] * o0[0] + o0[1] * o0[1]) + (o0[2] * o0[2] + o0[3] * o0[3])) + ((o1[0] * o1[0] + o1[1] * o1[1]) + (o1[2] * o1[2] + o1[3] * o1[3]));
;                     u32x4 w; w.x = cvt_pk_bf16(o0[0], o0[1]); w.y = cvt_pk_bf16(o0[2], o0[3]); w.z = cvt_pk_bf16(o1[0], o1[1]); w.w = cvt_pk_bf16(o1[2], o1[3]);
;                     *(u32x4*)(HB + off + bj * HALF) = w; }
;                 ss += __shfl_xor(ss, 16); ss += __shfl_xor(ss, 32);
;                 if (fq == 0) PS[(size_t)row * 16 + u.pn * 4 + wc] = ss; }
.LBB0_1103:
	v_mul_f32_e32 v104, v109, v109
	v_mul_f32_e32 v95, v95, v95
	v_pk_add_f32 v[74:75], v[74:75], v[82:83]
	v_pk_add_f32 v[72:73], v[72:73], v[80:81]
	v_fmac_f32_e32 v104, v108, v108
	v_fmac_f32_e32 v95, v94, v94
	v_pk_add_f32 v[82:83], v[68:69], v[84:85]
	v_mul_f32_e32 v68, v73, v73
	v_mul_f32_e32 v69, v75, v75
	v_add_f32_e32 v94, v104, v95
	v_mul_f32_e32 v95, v97, v97
	v_pk_add_f32 v[80:81], v[70:71], v[86:87]
	v_fmac_f32_e32 v68, v72, v72
	v_fmac_f32_e32 v69, v74, v74
	v_fmac_f32_e32 v95, v96, v96
	v_mul_f32_e32 v96, v99, v99
	v_add_f32_e32 v68, v68, v69
	v_mul_f32_e32 v69, v83, v83
	v_mul_f32_e32 v70, v81, v81
	v_fmac_f32_e32 v96, v98, v98
	v_fmac_f32_e32 v69, v82, v82
	v_fmac_f32_e32 v70, v80, v80
	v_add_f32_e32 v95, v95, v96
	v_add_f32_e32 v69, v69, v70
	v_add_f32_e32 v94, v94, v95
	v_add_f32_e32 v68, v68, v69
	v_add_f32_e32 v68, v94, v68
	ds_bpermute_b32 v69, v184, v68
	v_cvt_pk_bf16_f32 v70, v72, v73
	v_cvt_pk_bf16_f32 v71, v74, v75
	v_cvt_pk_bf16_f32 v72, v82, v83
	v_cvt_pk_bf16_f32 v73, v80, v81
	s_waitcnt lgkmcnt(0)
	v_add_f32_e32 v68, v68, v69
	ds_bpermute_b32 v69, v158, v68
	global_store_dwordx4 v[92:93], v[70:73], off offset:256
	s_and_saveexec_b64 s[36:37], s[0:1]
	s_cbranch_execz .LBB0_1105
	v_lshlrev_b64 v[70:71], 6, v[224:225]
	v_lshl_add_u64 v[70:71], s[26:27], 0, v[70:71]
	v_lshl_add_u64 v[70:71], s[34:35], 2, v[70:71]
	s_lshl_b32 s10, s45, 2
	v_lshl_add_u64 v[70:71], v[70:71], 0, s[10:11]
	s_waitcnt lgkmcnt(0)
	v_add_f32_e32 v68, v68, v69
	global_store_dword v[70:71], v68, off
.LBB0_1105:
	s_or_b64 exec, exec, s[36:37]
	v_add_u32_e32 v80, 0x80, v220
	v_ashrrev_i32_e32 v81, 31, v80
	s_waitcnt lgkmcnt(0)
	v_lshlrev_b64 v[68:69], 10, v[80:81]
	v_lshl_add_u64 v[84:85], v[68:69], 0, v[222:223]
	s_and_b64 vcc, exec, s[4:5]
	v_lshl_add_u64 v[82:83], v[84:85], 2, s[60:61]
	s_cbranch_vccnz .LBB0_1148
	s_waitcnt vmcnt(6)
	v_mov_b64 v[68:69], v[148:149]
	v_mov_b64 v[70:71], v[150:151]
	v_mov_b64 v[72:73], v[136:137]
	v_mov_b64 v[74:75], v[138:139]
	s_cbranch_execnz .LBB0_1108

; __device__ __forceinline__ unsigned cvt_pk_bf16(float lo, float hi) { return pk2(lo, hi); }
;     __device__ __forceinline__ void operator()(const f32x4 (&acc)[2][2][4][2], const Unit& u, long coff, int wr, int wc, int fr, int fq, LAS unsigned char* xl) const {
;     ...
;                 for (int bj = 0; bj < 2; ++bj) { f32x4 b0, b1;
;                     if (basef) { b0 = *(const f32x4*)(basef + off + bj * HALF); b1 = *(const f32x4*)(basef + off + bj * HALF + 4); }
;                     else { const u32x4 h4 = hb[ai][m][bj]; b0 = (f32x4){bflo(h4.x), bfhi(h4.x), bflo(h4.y), bfhi(h4.y)}; b1 = (f32x4){bflo(h4.z), bfhi(h4.z), bflo(h4.w), bfhi(h4.w)}; }
;                     const f32x4 o0 = b0 + acc[ai][bj][m][0], o1 = b1 + acc[ai][bj][m][1];
;                     ss += ((o0[0] * o0[0] + o0[1] * o0[1]) + (o0[2] * o0[2] + o0[3] * o0[3])) + ((o1[0] * o1[0] + o1[1] * o1[1]) + (o1[2] * o1[2] + o1[3] * o1[3]));
;                     u32x4 w; w.x = cvt_pk_bf16(o0[0], o0[1]); w.y = cvt_pk_bf16(o0[2], o0[3]); w.z = cvt_pk_bf16(o1[0], o1[1]); w.w = cvt_pk_bf16(o1[2], o1[3]);
;                     *(u32x4*)(HB + off + bj * HALF) = w; }
.LBB0_1108:
	v_readlane_b32 s36, v253, 21
	v_pk_add_f32 v[70:71], v[62:63], v[70:71]
	v_pk_add_f32 v[86:87], v[60:61], v[68:69]
	v_pk_add_f32 v[74:75], v[58:59], v[74:75]
	v_pk_add_f32 v[72:73], v[56:57], v[72:73]
	v_readlane_b32 s37, v253, 22
	v_cvt_pk_bf16_f32 v56, v86, v87
	v_cvt_pk_bf16_f32 v57, v70, v71
	v_cvt_pk_bf16_f32 v58, v72, v73
	v_cvt_pk_bf16_f32 v59, v74, v75
	v_lshl_add_u64 v[68:69], v[84:85], 1, s[36:37]
	s_and_b64 vcc, exec, s[4:5]
	global_store_dwordx4 v[68:69], v[56:59], off
	s_cbranch_vccnz .LBB0_1149
	s_waitcnt vmcnt(4)
	v_mov_b64 v[56:57], v[124:125]
	v_mov_b64 v[58:59], v[126:127]
	v_mov_b64 v[60:61], v[112:113]
	v_mov_b64 v[62:63], v[114:115]
	s_cbranch_execnz .LBB0_1111

; __device__ __forceinline__ unsigned cvt_pk_bf16(float lo, float hi) { return pk2(lo, hi); }
;     __device__ __forceinline__ void operator()(const f32x4 (&acc)[2][2][4][2], const Unit& u, long coff, int wr, int wc, int fr, int fq, LAS unsigned char* xl) const {
;     ...
;             for (int m = 0; m < 4; ++m) { const int row = rowb + ai * HALF + m * 16; const size_t off = (size_t)row * ldc + col0; float ss = 0.f;
;     ...
;                     const f32x4 o0 = b0 + acc[ai][bj][m][0], o1 = b1 + acc[ai][bj][m][1];
;                     ss += ((o0[0] * o0[0] + o0[1] * o0[1]) + (o0[2] * o0[2] + o0[3] * o0[3])) + ((o1[0] * o1[0] + o1[1] * o1[1]) + (o1[2] * o1[2] + o1[3] * o1[3]));
;                     u32x4 w; w.x = cvt_pk_bf16(o0[0], o0[1]); w.y = cvt_pk_bf16(o0[2], o0[3]); w.z = cvt_pk_bf16(o1[0], o1[1]); w.w = cvt_pk_bf16(o1[2], o1[3]);
;                     *(u32x4*)(HB + off + bj * HALF) = w; }
;                 ss += __shfl_xor(ss, 16); ss += __shfl_xor(ss, 32);
;                 if (fq == 0) PS[(size_t)row * 16 + u.pn * 4 + wc] = ss; }
.LBB0_1111:
	v_mul_f32_e32 v82, v87, v87
	v_mul_f32_e32 v71, v71, v71
	v_pk_add_f32 v[54:55], v[54:55], v[58:59]
	v_pk_add_f32 v[52:53], v[52:53], v[56:57]
	v_fmac_f32_e32 v82, v86, v86
	v_fmac_f32_e32 v71, v70, v70
	v_pk_add_f32 v[58:59], v[48:49], v[60:61]
	v_mul_f32_e32 v48, v53, v53
	v_mul_f32_e32 v49, v55, v55
	v_add_f32_e32 v70, v82, v71
	v_mul_f32_e32 v71, v73, v73
	v_pk_add_f32 v[56:57], v[50:51], v[62:63]
	v_fmac_f32_e32 v48, v52, v52
	v_fmac_f32_e32 v49, v54, v54
	v_fmac_f32_e32 v71, v72, v72
	v_mul_f32_e32 v72, v75, v75
	v_add_f32_e32 v48, v48, v49
	v_mul_f32_e32 v49, v59, v59
	v_mul_f32_e32 v50, v57, v57
	v_fmac_f32_e32 v72, v74, v74
	v_fmac_f32_e32 v49, v58, v58
	v_fmac_f32_e32 v50, v56, v56
	v_add_f32_e32 v71, v71, v72
	v_add_f32_e32 v49, v49, v50
	v_add_f32_e32 v70, v70, v71
	v_add_f32_e32 v48, v48, v49
	v_add_f32_e32 v48, v70, v48
	ds_bpermute_b32 v49, v184, v48
	v_cvt_pk_bf16_f32 v50, v52, v53
	v_cvt_pk_bf16_f32 v51, v54, v55
	v_cvt_pk_bf16_f32 v52, v58, v59
	v_cvt_pk_bf16_f32 v53, v56, v57
	s_waitcnt lgkmcnt(0)
	v_add_f32_e32 v48, v48, v49
	ds_bpermute_b32 v49, v158, v48
	global_store_dwordx4 v[68:69], v[50:53], off offset:256
	s_and_saveexec_b64 s[36:37], s[0:1]
	s_cbranch_execz .LBB0_1113
	v_lshlrev_b64 v[50:51], 6, v[80:81]
	v_lshl_add_u64 v[50:51], s[26:27], 0, v[50:51]
	v_lshl_add_u64 v[50:51], s[34:35], 2, v[50:51]
	s_lshl_b32 s10, s45, 2
	v_lshl_add_u64 v[50:51], v[50:51], 0, s[10:11]
	s_waitcnt lgkmcnt(0)
	v_add_f32_e32 v48, v48, v49
	global_store_dword v[50:51], v48, off
.LBB0_1113:
	s_or_b64 exec, exec, s[36:37]
	v_add_u32_e32 v56, 0x90, v220
	v_ashrrev_i32_e32 v57, 31, v56
	s_waitcnt lgkmcnt(0)
	v_lshlrev_b64 v[48:49], 10, v[56:57]
	v_lshl_add_u64 v[60:61], v[48:49], 0, v[222:223]
	s_and_b64 vcc, exec, s[4:5]
	v_lshl_add_u64 v[58:59], v[60:61], 2, s[60:61]
	s_cbranch_vccnz .LBB0_1150
	s_waitcnt vmcnt(2)
	v_mov_b64 v[48:49], v[100:101]
	v_mov_b64 v[50:51], v[102:103]
	v_mov_b64 v[52:53], v[88:89]
	v_mov_b64 v[54:55], v[90:91]
	s_cbranch_execnz .LBB0_1116

; __device__ __forceinline__ unsigned cvt_pk_bf16(float lo, float hi) { return pk2(lo, hi); }
;     __device__ __forceinline__ void operator()(const f32x4 (&acc)[2][2][4][2], const Unit& u, long coff, int wr, int wc, int fr, int fq, LAS unsigned char* xl) const {
;     ...
;                 for (int bj = 0; bj < 2; ++bj) { f32x4 b0, b1;
;                     if (basef) { b0 = *(const f32x4*)(basef + off + bj * HALF); b1 = *(const f32x4*)(basef + off + bj * HALF + 4); }
;                     else { const u32x4 h4 = hb[ai][m][bj]; b0 = (f32x4){bflo(h4.x), bfhi(h4.x), bflo(h4.y), bfhi(h4.y)}; b1 = (f32x4){bflo(h4.z), bfhi(h4.z), bflo(h4.w), bfhi(h4.w)}; }
;                     const f32x4 o0 = b0 + acc[ai][bj][m][0], o1 = b1 + acc[ai][bj][m][1];
;                     ss += ((o0[0] * o0[0] + o0[1] * o0[1]) + (o0[2] * o0[2] + o0[3] * o0[3])) + ((o1[0] * o1[0] + o1[1] * o1[1]) + (o1[2] * o1[2] + o1[3] * o1[3]));
;                     u32x4 w; w.x = cvt_pk_bf16(o0[0], o0[1]); w.y = cvt_pk_bf16(o0[2], o0[3]); w.z = cvt_pk_bf16(o1[0], o1[1]); w.w = cvt_pk_bf16(o1[2], o1[3]);
;                     *(u32x4*)(HB + off + bj * HALF) = w; }
.LBB0_1116:
	v_readlane_b32 s36, v253, 21
	v_pk_add_f32 v[50:51], v[46:47], v[50:51]
	v_pk_add_f32 v[62:63], v[44:45], v[48:49]
	v_pk_add_f32 v[54:55], v[42:43], v[54:55]
	v_pk_add_f32 v[52:53], v[40:41], v[52:53]
	v_readlane_b32 s37, v253, 22
	v_cvt_pk_bf16_f32 v40, v62, v63
	v_cvt_pk_bf16_f32 v41, v50, v51
	v_cvt_pk_bf16_f32 v42, v52, v53
	v_cvt_pk_bf16_f32 v43, v54, v55
	v_lshl_add_u64 v[48:49], v[60:61], 1, s[36:37]
	s_and_b64 vcc, exec, s[4:5]
	global_store_dwordx4 v[48:49], v[40:43], off
	s_cbranch_vccnz .LBB0_1151
	s_waitcnt vmcnt(0)
	v_mov_b64 v[40:41], v[76:77]
	v_mov_b64 v[42:43], v[78:79]
	v_mov_b64 v[44:45], v[64:65]
	v_mov_b64 v[46:47], v[66:67]
	s_cbranch_execnz .LBB0_1119

; __device__ __forceinline__ unsigned cvt_pk_bf16(float lo, float hi) { return pk2(lo, hi); }
;     __device__ __forceinline__ void operator()(const f32x4 (&acc)[2][2][4][2], const Unit& u, long coff, int wr, int wc, int fr, int fq, LAS unsigned char* xl) const {
;     ...
;                     const f32x4 o0 = b0 + acc[ai][bj][m][0], o1 = b1 + acc[ai][bj][m][1];
;                     ss += ((o0[0] * o0[0] + o0[1] * o0[1]) + (o0[2] * o0[2] + o0[3] * o0[3])) + ((o1[0] * o1[0] + o1[1] * o1[1]) + (o1[2] * o1[2] + o1[3] * o1[3]));
;                     u32x4 w; w.x = cvt_pk_bf16(o0[0], o0[1]); w.y = cvt_pk_bf16(o0[2], o0[3]); w.z = cvt_pk_bf16(o1[0], o1[1]); w.w = cvt_pk_bf16(o1[2], o1[3]);
;                     *(u32x4*)(HB + off + bj * HALF) = w; }
;                 ss += __shfl_xor(ss, 16); ss += __shfl_xor(ss, 32);
;                 if (fq == 0) PS[(size_t)row * 16 + u.pn * 4 + wc] = ss; }
.LBB0_1119:
	v_mul_f32_e32 v58, v63, v63
	v_mul_f32_e32 v51, v51, v51
	v_pk_add_f32 v[38:39], v[38:39], v[42:43]
	v_pk_add_f32 v[36:37], v[36:37], v[40:41]
	v_fmac_f32_e32 v58, v62, v62
	v_fmac_f32_e32 v51, v50, v50
	v_pk_add_f32 v[42:43], v[32:33], v[44:45]
	v_mul_f32_e32 v32, v37, v37
	v_mul_f32_e32 v33, v39, v39
	v_add_f32_e32 v50, v58, v51
	v_mul_f32_e32 v51, v53, v53
	v_pk_add_f32 v[40:41], v[34:35], v[46:47]
	v_fmac_f32_e32 v32, v36, v36
	v_fmac_f32_e32 v33, v38, v38
	v_fmac_f32_e32 v51, v52, v52
	v_mul_f32_e32 v52, v55, v55
	v_add_f32_e32 v32, v32, v33
	v_mul_f32_e32 v33, v43, v43
	v_mul_f32_e32 v34, v41, v41
	v_fmac_f32_e32 v52, v54, v54
	v_fmac_f32_e32 v33, v42, v42
	v_fmac_f32_e32 v34, v40, v40
	v_add_f32_e32 v51, v51, v52
	v_add_f32_e32 v33, v33, v34
	v_add_f32_e32 v50, v50, v51
	v_add_f32_e32 v32, v32, v33
	v_add_f32_e32 v32, v50, v32
	ds_bpermute_b32 v33, v184, v32
	v_cvt_pk_bf16_f32 v34, v36, v37
	v_cvt_pk_bf16_f32 v35, v38, v39
	v_cvt_pk_bf16_f32 v36, v42, v43
	v_cvt_pk_bf16_f32 v37, v40, v41
	s_waitcnt lgkmcnt(0)
	v_add_f32_e32 v32, v32, v33
	ds_bpermute_b32 v33, v158, v32
	global_store_dwordx4 v[48:49], v[34:37], off offset:256
	s_and_saveexec_b64 s[36:37], s[0:1]
	s_cbranch_execz .LBB0_1121
	v_lshlrev_b64 v[34:35], 6, v[56:57]
	v_lshl_add_u64 v[34:35], s[26:27], 0, v[34:35]
	v_lshl_add_u64 v[34:35], s[34:35], 2, v[34:35]
	s_lshl_b32 s10, s45, 2
	v_lshl_add_u64 v[34:35], v[34:35], 0, s[10:11]
	s_waitcnt lgkmcnt(0)
	v_add_f32_e32 v32, v32, v33
	global_store_dword v[34:35], v32, off
